# speedup vs baseline: 1.0464x; 1.0459x over previous
; __device__ __forceinline__ float bf_lo(unsigned u) { return __uint_as_float(u << 16); }
; __device__ __forceinline__ float bf_hi(unsigned u) { return __uint_as_float(u & 0xffff0000u); }
; __global__ __launch_bounds__(512, 2)
; void hybrid_megakernel(Params p_in) {
;     ...
;         for (int tk = gw; tk < NTOK; tk += nw) {
;           const bf16* pr = proj + (long)tk * INC + OFF_Q + lane * 8;
;           u32x4 w[8];
; #pragma unroll
;           for (int i = 0; i < 8; ++i) w[i] = *reinterpret_cast<const u32x4*>(pr + i * 512);
; #pragma unroll
;           for (int i = 0; i < 8; ++i) {
;             float ss = 0.f;
; #pragma unroll
;             for (int q = 0; q < 4; ++q) { const float a = bf_lo(w[i][q]), b2 = bf_hi(w[i][q]); ss += a * a + b2 * b2; }
;             ss += __shfl_xor(ss, 1, 64); ss += __shfl_xor(ss, 2, 64); ss += __shfl_xor(ss, 4, 64); ss += __shfl_xor(ss, 8, 64);
;             mx[i] = fmaxf(mx[i], ss);
;           }
; #pragma unroll
;           for (int i = 0; i < 4; ++i) {
;             float dt = 0.f;
; #pragma unroll
;             for (int q = 0; q < 4; ++q) dt += bf_lo(w[i][q]) * bf_lo(w[i + 4][q]) + bf_hi(w[i][q]) * bf_hi(w[i + 4][q]);
;             dt += __shfl_xor(dt, 1, 64); dt += __shfl_xor(dt, 2, 64); dt += __shfl_xor(dt, 4, 64); dt += __shfl_xor(dt, 8, 64);
;             ms[i] = fmaxf(ms[i], -dt);
;           }
.LBB0_104:
	v_add_co_u32_e32 v4, vcc, 0xfffff000, v0
	v_max_f32_e32 v40, v40, v40
	s_nop 0
	v_addc_co_u32_e32 v5, vcc, -1, v1, vcc
	global_load_dwordx4 v[28:31], v[4:5], off offset:-3072
	global_load_dwordx4 v[24:27], v[4:5], off offset:-2048
	global_load_dwordx4 v[16:19], v[4:5], off offset:-1024
	global_load_dwordx4 v[8:11], v[0:1], off offset:-4096
	global_load_dwordx4 v[48:51], v[0:1], off offset:-3072
	global_load_dwordx4 v[20:23], v[0:1], off offset:-2048
	global_load_dwordx4 v[12:15], v[0:1], off offset:-1024
	s_nop 0
	global_load_dwordx4 v[4:7], v[0:1], off
	s_add_i32 s11, s10, s62
	s_cmpk_gt_i32 s11, 0x3fff
	s_cselect_b64 s[0:1], -1, 0
	s_cmpk_lt_i32 s11, 0x4000
	s_cselect_b64 s[2:3], -1, 0
	s_xor_b32 s14, s11, s10
	s_cmpk_lt_u32 s14, 0x2000
	s_cselect_b64 s[14:15], -1, 0
	v_max_f32_e32 v44, v44, v44
	s_and_b64 s[2:3], s[2:3], s[14:15]
	s_and_b64 vcc, exec, s[2:3]
	s_waitcnt vmcnt(0)
	v_lshlrev_b32_e32 v53, 16, v29
	v_lshlrev_b32_e32 v52, 16, v28
	v_and_b32_e32 v29, 0xffff0000, v29
	v_and_b32_e32 v28, 0xffff0000, v28
	v_lshlrev_b32_e32 v57, 16, v49
	v_lshlrev_b32_e32 v56, 16, v48
	v_and_b32_e32 v49, 0xffff0000, v49
	v_and_b32_e32 v48, 0xffff0000, v48
	v_pk_mul_f32 v[54:55], v[28:29], v[28:29]
	v_pk_mul_f32 v[28:29], v[28:29], v[48:49]
	v_pk_mul_f32 v[58:59], v[48:49], v[48:49]
	v_pk_fma_f32 v[28:29], v[52:53], v[56:57], v[28:29]
	v_pk_fma_f32 v[58:59], v[56:57], v[56:57], v[58:59]
	v_add_f32_e32 v28, 0, v28
	v_add_f32_e32 v56, v28, v29
	v_lshlrev_b32_e32 v29, 16, v31
	v_lshlrev_b32_e32 v28, 16, v30
	v_and_b32_e32 v31, 0xffff0000, v31
	v_and_b32_e32 v30, 0xffff0000, v30
	v_pk_fma_f32 v[54:55], v[52:53], v[52:53], v[54:55]
	v_pk_mul_f32 v[48:49], v[30:31], v[30:31]
	v_add_f32_e32 v52, v54, v55
	v_pk_fma_f32 v[48:49], v[28:29], v[28:29], v[48:49]
	v_add_f32_e32 v54, v58, v59
	v_add_f32_e32 v48, v52, v48
	v_add_f32_e32 v48, v48, v49
	ds_bpermute_b32 v49, v2, v48
	s_waitcnt lgkmcnt(0)
	v_add_f32_e32 v48, v48, v49
	ds_bpermute_b32 v49, v32, v48
	s_waitcnt lgkmcnt(0)
	v_add_f32_e32 v48, v48, v49
	ds_bpermute_b32 v49, v33, v48
	s_waitcnt lgkmcnt(0)
	v_add_f32_e32 v48, v48, v49
	ds_bpermute_b32 v49, v34, v48
	s_waitcnt lgkmcnt(0)
	v_add_f32_e32 v48, v48, v49
	v_max_f32_e32 v40, v40, v48
	v_lshlrev_b32_e32 v49, 16, v51
	v_lshlrev_b32_e32 v48, 16, v50
	v_and_b32_e32 v51, 0xffff0000, v51
	v_and_b32_e32 v50, 0xffff0000, v50
	v_pk_mul_f32 v[30:31], v[30:31], v[50:51]
	v_pk_mul_f32 v[52:53], v[50:51], v[50:51]
	v_pk_fma_f32 v[28:29], v[28:29], v[48:49], v[30:31]
	v_lshlrev_b32_e32 v31, 16, v25
	v_add_f32_e32 v28, v56, v28
	v_add_f32_e32 v28, v28, v29
	ds_bpermute_b32 v29, v2, v28
	v_lshlrev_b32_e32 v30, 16, v24
	v_and_b32_e32 v25, 0xffff0000, v25
	v_and_b32_e32 v24, 0xffff0000, v24
	v_lshlrev_b32_e32 v51, 16, v21
	s_waitcnt lgkmcnt(0)
	v_add_f32_e32 v28, v28, v29
	ds_bpermute_b32 v29, v32, v28
	v_lshlrev_b32_e32 v50, 16, v20
	v_and_b32_e32 v21, 0xffff0000, v21
	v_and_b32_e32 v20, 0xffff0000, v20
	v_pk_fma_f32 v[52:53], v[48:49], v[48:49], v[52:53]
	s_waitcnt lgkmcnt(0)
	v_add_f32_e32 v28, v28, v29
	ds_bpermute_b32 v29, v33, v28
	v_add_f32_e32 v52, v54, v52
	v_add_f32_e32 v52, v52, v53
	ds_bpermute_b32 v53, v2, v52
	s_waitcnt lgkmcnt(1)
	v_add_f32_e32 v28, v28, v29
	ds_bpermute_b32 v29, v34, v28
	s_waitcnt lgkmcnt(1)
	v_add_f32_e32 v52, v52, v53
	ds_bpermute_b32 v53, v32, v52
	s_waitcnt lgkmcnt(1)
	v_add_f32_e32 v28, v28, v29
	v_max_f32_e32 v29, v36, v36
	v_max_f32_e64 v36, v29, -v28
	v_pk_mul_f32 v[28:29], v[24:25], v[24:25]
	s_waitcnt lgkmcnt(0)
	v_add_f32_e32 v52, v52, v53
	v_pk_fma_f32 v[48:49], v[30:31], v[30:31], v[28:29]
	v_pk_mul_f32 v[28:29], v[20:21], v[20:21]
	v_pk_mul_f32 v[20:21], v[24:25], v[20:21]
	v_and_b32_e32 v25, 0xffff0000, v27
	v_pk_fma_f32 v[20:21], v[30:31], v[50:51], v[20:21]
	v_and_b32_e32 v24, 0xffff0000, v26
	v_add_f32_e32 v20, 0, v20
	v_add_f32_e32 v30, v20, v21
	v_lshlrev_b32_e32 v21, 16, v27
	v_lshlrev_b32_e32 v20, 16, v26
	v_pk_mul_f32 v[26:27], v[24:25], v[24:25]
	v_add_f32_e32 v31, v48, v49
	v_pk_fma_f32 v[26:27], v[20:21], v[20:21], v[26:27]
	v_pk_fma_f32 v[28:29], v[50:51], v[50:51], v[28:29]
	v_add_f32_e32 v26, v31, v26
	v_add_f32_e32 v26, v26, v27
	ds_bpermute_b32 v27, v2, v26
	v_add_f32_e32 v28, v28, v29
	ds_bpermute_b32 v53, v33, v52
	s_waitcnt lgkmcnt(1)
	v_add_f32_e32 v26, v26, v27
	ds_bpermute_b32 v27, v32, v26
	s_waitcnt lgkmcnt(1)
	v_add_f32_e32 v52, v52, v53
	ds_bpermute_b32 v53, v34, v52
	s_waitcnt lgkmcnt(1)
	v_add_f32_e32 v26, v26, v27
	ds_bpermute_b32 v27, v33, v26
	s_waitcnt lgkmcnt(1)
	v_add_f32_e32 v52, v52, v53
	v_max_f32_e32 v44, v44, v52
	s_waitcnt lgkmcnt(0)
	v_add_f32_e32 v26, v26, v27
	ds_bpermute_b32 v27, v34, v26
	s_waitcnt lgkmcnt(0)
	v_add_f32_e32 v26, v26, v27
	v_max_f32_e32 v27, v41, v41
	v_max_f32_e32 v41, v27, v26
	v_lshlrev_b32_e32 v27, 16, v23
	v_lshlrev_b32_e32 v26, 16, v22
	v_and_b32_e32 v23, 0xffff0000, v23
	v_and_b32_e32 v22, 0xffff0000, v22
	v_pk_mul_f32 v[48:49], v[22:23], v[22:23]
	v_pk_mul_f32 v[22:23], v[24:25], v[22:23]
	v_lshlrev_b32_e32 v25, 16, v13
	v_pk_fma_f32 v[20:21], v[20:21], v[26:27], v[22:23]
	v_lshlrev_b32_e32 v24, 16, v12
	v_add_f32_e32 v20, v30, v20
	v_add_f32_e32 v20, v20, v21
	ds_bpermute_b32 v21, v2, v20
	v_and_b32_e32 v13, 0xffff0000, v13
	v_and_b32_e32 v12, 0xffff0000, v12
	v_pk_fma_f32 v[48:49], v[26:27], v[26:27], v[48:49]
	v_pk_mul_f32 v[26:27], v[12:13], v[12:13]
	s_waitcnt lgkmcnt(0)
	v_add_f32_e32 v20, v20, v21
	ds_bpermute_b32 v21, v32, v20
	v_pk_fma_f32 v[26:27], v[24:25], v[24:25], v[26:27]
	v_add_f32_e32 v28, v28, v48
	v_add_f32_e32 v28, v28, v49
	ds_bpermute_b32 v29, v2, v28
	s_waitcnt lgkmcnt(1)
; __device__ __forceinline__ float bf_lo(unsigned u) { return __uint_as_float(u << 16); }
; __device__ __forceinline__ float bf_hi(unsigned u) { return __uint_as_float(u & 0xffff0000u); }
; __global__ __launch_bounds__(512, 2)
; void hybrid_megakernel(Params p_in) {
;     ...
;         for (int tk = gw; tk < NTOK; tk += nw) {
;           const bf16* pr = proj + (long)tk * INC + OFF_Q + lane * 8;
;           u32x4 w[8];
; #pragma unroll
;           for (int i = 0; i < 8; ++i) w[i] = *reinterpret_cast<const u32x4*>(pr + i * 512);
; #pragma unroll
;           for (int i = 0; i < 8; ++i) {
;             float ss = 0.f;
; #pragma unroll
;             for (int q = 0; q < 4; ++q) { const float a = bf_lo(w[i][q]), b2 = bf_hi(w[i][q]); ss += a * a + b2 * b2; }
;             ss += __shfl_xor(ss, 1, 64); ss += __shfl_xor(ss, 2, 64); ss += __shfl_xor(ss, 4, 64); ss += __shfl_xor(ss, 8, 64);
;             mx[i] = fmaxf(mx[i], ss);
;           }
; #pragma unroll
;           for (int i = 0; i < 4; ++i) {
;             float dt = 0.f;
; #pragma unroll
;             for (int q = 0; q < 4; ++q) dt += bf_lo(w[i][q]) * bf_lo(w[i + 4][q]) + bf_hi(w[i][q]) * bf_hi(w[i + 4][q]);
;             dt += __shfl_xor(dt, 1, 64); dt += __shfl_xor(dt, 2, 64); dt += __shfl_xor(dt, 4, 64); dt += __shfl_xor(dt, 8, 64);
;             ms[i] = fmaxf(ms[i], -dt);
;           }
;           if (tk + nw >= NTOK || ((tk + nw) >> 13) != (tk >> 13)) {
	v_add_f32_e32 v20, v20, v21
	ds_bpermute_b32 v21, v33, v20
	s_waitcnt lgkmcnt(1)
	v_add_f32_e32 v28, v28, v29
	ds_bpermute_b32 v29, v32, v28
	s_waitcnt lgkmcnt(1)
	v_add_f32_e32 v20, v20, v21
	ds_bpermute_b32 v21, v34, v20
	s_waitcnt lgkmcnt(1)
	v_add_f32_e32 v28, v28, v29
	ds_bpermute_b32 v29, v33, v28
	s_waitcnt lgkmcnt(1)
	v_add_f32_e32 v20, v20, v21
	v_max_f32_e32 v21, v37, v37
	v_max_f32_e64 v37, v21, -v20
	v_lshlrev_b32_e32 v21, 16, v17
	v_lshlrev_b32_e32 v20, 16, v16
	v_and_b32_e32 v17, 0xffff0000, v17
	v_and_b32_e32 v16, 0xffff0000, v16
	v_pk_mul_f32 v[12:13], v[16:17], v[12:13]
	v_pk_mul_f32 v[22:23], v[16:17], v[16:17]
	v_pk_fma_f32 v[12:13], v[20:21], v[24:25], v[12:13]
	v_and_b32_e32 v17, 0xffff0000, v19
	v_add_f32_e32 v12, 0, v12
	v_and_b32_e32 v16, 0xffff0000, v18
	v_pk_fma_f32 v[22:23], v[20:21], v[20:21], v[22:23]
	v_add_f32_e32 v24, v12, v13
	v_lshlrev_b32_e32 v13, 16, v19
	v_lshlrev_b32_e32 v12, 16, v18
	v_pk_mul_f32 v[18:19], v[16:17], v[16:17]
	v_add_f32_e32 v20, v22, v23
	v_pk_fma_f32 v[18:19], v[12:13], v[12:13], v[18:19]
	v_add_f32_e32 v22, v26, v27
	v_add_f32_e32 v18, v20, v18
	v_add_f32_e32 v18, v18, v19
	ds_bpermute_b32 v19, v2, v18
	s_waitcnt lgkmcnt(1)
	v_add_f32_e32 v28, v28, v29
	ds_bpermute_b32 v29, v34, v28
	s_waitcnt lgkmcnt(1)
	v_add_f32_e32 v18, v18, v19
	ds_bpermute_b32 v19, v32, v18
	s_waitcnt lgkmcnt(1)
	v_add_f32_e32 v28, v28, v29
	v_max_f32_e32 v29, v45, v45
	v_max_f32_e32 v45, v29, v28
	s_waitcnt lgkmcnt(0)
	v_add_f32_e32 v18, v18, v19
	ds_bpermute_b32 v19, v33, v18
	s_waitcnt lgkmcnt(0)
	v_add_f32_e32 v18, v18, v19
	ds_bpermute_b32 v19, v34, v18
	s_waitcnt lgkmcnt(0)
	v_add_f32_e32 v18, v18, v19
	v_max_f32_e32 v19, v42, v42
	v_max_f32_e32 v42, v19, v18
	v_lshlrev_b32_e32 v19, 16, v15
	v_lshlrev_b32_e32 v18, 16, v14
	v_and_b32_e32 v15, 0xffff0000, v15
	v_and_b32_e32 v14, 0xffff0000, v14
	v_pk_mul_f32 v[20:21], v[14:15], v[14:15]
	v_pk_mul_f32 v[14:15], v[16:17], v[14:15]
	v_lshlrev_b32_e32 v17, 16, v5
	v_pk_fma_f32 v[12:13], v[12:13], v[18:19], v[14:15]
	v_lshlrev_b32_e32 v16, 16, v4
	v_add_f32_e32 v12, v24, v12
	v_add_f32_e32 v12, v12, v13
	ds_bpermute_b32 v13, v2, v12
	v_and_b32_e32 v5, 0xffff0000, v5
	v_and_b32_e32 v4, 0xffff0000, v4
	v_pk_fma_f32 v[20:21], v[18:19], v[18:19], v[20:21]
	v_pk_mul_f32 v[18:19], v[4:5], v[4:5]
	s_waitcnt lgkmcnt(0)
	v_add_f32_e32 v12, v12, v13
	ds_bpermute_b32 v13, v32, v12
	v_pk_fma_f32 v[18:19], v[16:17], v[16:17], v[18:19]
	v_add_f32_e32 v20, v22, v20
	v_add_f32_e32 v20, v20, v21
	ds_bpermute_b32 v21, v2, v20
	s_waitcnt lgkmcnt(1)
	v_add_f32_e32 v12, v12, v13
	ds_bpermute_b32 v13, v33, v12
	s_waitcnt lgkmcnt(1)
	v_add_f32_e32 v20, v20, v21
	ds_bpermute_b32 v21, v32, v20
	s_waitcnt lgkmcnt(1)
	v_add_f32_e32 v12, v12, v13
	ds_bpermute_b32 v13, v34, v12
	s_waitcnt lgkmcnt(1)
	v_add_f32_e32 v20, v20, v21
	ds_bpermute_b32 v21, v33, v20
	s_waitcnt lgkmcnt(1)
	v_add_f32_e32 v12, v12, v13
	v_max_f32_e32 v13, v38, v38
	v_max_f32_e64 v38, v13, -v12
	v_lshlrev_b32_e32 v13, 16, v9
	v_lshlrev_b32_e32 v12, 16, v8
	v_and_b32_e32 v9, 0xffff0000, v9
	v_and_b32_e32 v8, 0xffff0000, v8
	v_pk_mul_f32 v[4:5], v[8:9], v[4:5]
	v_pk_mul_f32 v[14:15], v[8:9], v[8:9]
	v_pk_fma_f32 v[4:5], v[12:13], v[16:17], v[4:5]
	v_and_b32_e32 v9, 0xffff0000, v11
	v_add_f32_e32 v4, 0, v4
	v_and_b32_e32 v8, 0xffff0000, v10
	v_pk_fma_f32 v[14:15], v[12:13], v[12:13], v[14:15]
	v_add_f32_e32 v16, v4, v5
	v_lshlrev_b32_e32 v5, 16, v11
	v_lshlrev_b32_e32 v4, 16, v10
	v_pk_mul_f32 v[10:11], v[8:9], v[8:9]
	v_add_f32_e32 v12, v14, v15
	v_pk_fma_f32 v[10:11], v[4:5], v[4:5], v[10:11]
	v_add_f32_e32 v14, v18, v19
	v_add_f32_e32 v10, v12, v10
	v_add_f32_e32 v10, v10, v11
	ds_bpermute_b32 v11, v2, v10
	s_waitcnt lgkmcnt(1)
	v_add_f32_e32 v20, v20, v21
	ds_bpermute_b32 v21, v34, v20
	s_waitcnt lgkmcnt(1)
	v_add_f32_e32 v10, v10, v11
	ds_bpermute_b32 v11, v32, v10
	s_waitcnt lgkmcnt(1)
	v_add_f32_e32 v20, v20, v21
	v_max_f32_e32 v21, v46, v46
	v_max_f32_e32 v46, v21, v20
	s_waitcnt lgkmcnt(0)
	v_add_f32_e32 v10, v10, v11
	ds_bpermute_b32 v11, v33, v10
	s_waitcnt lgkmcnt(0)
	v_add_f32_e32 v10, v10, v11
	ds_bpermute_b32 v11, v34, v10
	s_waitcnt lgkmcnt(0)
	v_add_f32_e32 v10, v10, v11
	v_max_f32_e32 v11, v43, v43
	v_max_f32_e32 v43, v11, v10
	v_lshlrev_b32_e32 v11, 16, v7
	v_lshlrev_b32_e32 v10, 16, v6
	v_and_b32_e32 v7, 0xffff0000, v7
	v_and_b32_e32 v6, 0xffff0000, v6
	v_pk_mul_f32 v[12:13], v[6:7], v[6:7]
	v_pk_mul_f32 v[6:7], v[8:9], v[6:7]
	v_pk_fma_f32 v[12:13], v[10:11], v[10:11], v[12:13]
	v_pk_fma_f32 v[4:5], v[4:5], v[10:11], v[6:7]
	v_add_f32_e32 v12, v14, v12
	v_add_f32_e32 v4, v16, v4
	v_add_f32_e32 v12, v12, v13
	v_add_f32_e32 v4, v4, v5
	ds_bpermute_b32 v13, v2, v12
	ds_bpermute_b32 v5, v2, v4
	s_waitcnt lgkmcnt(1)
	v_add_f32_e32 v12, v12, v13
	s_waitcnt lgkmcnt(0)
	v_add_f32_e32 v4, v4, v5
	ds_bpermute_b32 v13, v32, v12
	ds_bpermute_b32 v5, v32, v4
	s_waitcnt lgkmcnt(1)
	v_add_f32_e32 v12, v12, v13
	s_waitcnt lgkmcnt(0)
	v_add_f32_e32 v4, v4, v5
	ds_bpermute_b32 v13, v33, v12
	ds_bpermute_b32 v5, v33, v4
	s_waitcnt lgkmcnt(1)
	v_add_f32_e32 v12, v12, v13
	s_waitcnt lgkmcnt(0)
	v_add_f32_e32 v4, v4, v5
	ds_bpermute_b32 v13, v34, v12
	ds_bpermute_b32 v5, v34, v4
	s_waitcnt lgkmcnt(1)
	v_add_f32_e32 v12, v12, v13
	v_max_f32_e32 v13, v47, v47
	s_waitcnt lgkmcnt(0)
	v_add_f32_e32 v4, v4, v5
	v_max_f32_e32 v5, v39, v39
	v_max_f32_e32 v47, v13, v12
	v_max_f32_e64 v39, v5, -v4
	s_cbranch_vccnz .LBB0_103
; __global__ __launch_bounds__(512, 2)
; void hybrid_megakernel(Params p_in) {
;     ...
;           if (tk + nw >= NTOK || ((tk + nw) >> 13) != (tk >> 13)) {
;             if ((lane & 15) == 0) {
; #pragma unroll
;               for (int i = 0; i < 8; ++i) atomicMax(&nrm[(tk >> 13) * 32 + (lane >> 4) + 4 * i], __float_as_uint(mx[i]));
; #pragma unroll
;               for (int i = 0; i < 4; ++i) atomicMax(&nself[(tk >> 13) * 16 + (lane >> 4) + 4 * i], __float_as_uint(ms[i]));
;             }
; #pragma unroll
;             for (int i = 0; i < 8; ++i) mx[i] = 0.f;
; #pragma unroll
;             for (int i = 0; i < 4; ++i) ms[i] = 0.f;
;           }
	s_cmpk_lg_i32 s52, 0x100
	s_cbranch_scc1 .Lmn_old
	v_readlane_b32 s14, v255, 3
	s_mul_i32 s15, s14, 0xc0
	s_add_i32 s15, s15, 0x22000
	s_and_saveexec_b64 s[2:3], s[4:5]
	v_lshl_add_u32 v4, v35, 2, s15
	ds_write_b32 v4, v40
	ds_write_b32 v4, v41 offset:16
	ds_write_b32 v4, v42 offset:32
	ds_write_b32 v4, v43 offset:48
	ds_write_b32 v4, v44 offset:64
	ds_write_b32 v4, v45 offset:80
	ds_write_b32 v4, v46 offset:96
	ds_write_b32 v4, v47 offset:112
	ds_write_b32 v4, v36 offset:128
	ds_write_b32 v4, v37 offset:144
	ds_write_b32 v4, v38 offset:160
	ds_write_b32 v4, v39 offset:176
	s_or_b64 exec, exec, s[2:3]
	s_waitcnt lgkmcnt(0)
	s_barrier
	s_cmp_lg_u32 s14, 0
	s_cbranch_scc1 .Lmn_wait
	v_cmp_gt_u32_e32 vcc, 48, v162
	s_and_saveexec_b64 s[2:3], vcc
	v_lshlrev_b32_e32 v4, 2, v162
	v_add_u32_e32 v5, 0x22000, v4
	ds_read_b32 v6, v5
	ds_read_b32 v7, v5 offset:192
	ds_read_b32 v8, v5 offset:384
	ds_read_b32 v9, v5 offset:576
	ds_read_b32 v10, v5 offset:768
	ds_read_b32 v11, v5 offset:960
	ds_read_b32 v12, v5 offset:1152
	ds_read_b32 v13, v5 offset:1344
	s_ashr_i32 s15, s10, 13
	s_lshl_b32 s16, s15, 7
	s_lshl_b32 s17, s15, 6
	v_cmp_gt_u32_e32 vcc, 32, v162
	v_add_u32_e32 v14, s16, v4
	v_add_u32_e32 v15, s17, v4
	v_subrev_u32_e32 v15, 0x80, v15
	v_mov_b32_e32 v16, s6
	v_mov_b32_e32 v17, s7
	v_mov_b32_e32 v18, s8
	v_mov_b32_e32 v19, s9
	v_cndmask_b32_e32 v14, v15, v14, vcc
	v_cndmask_b32_e32 v16, v18, v16, vcc
	v_cndmask_b32_e32 v17, v19, v17, vcc
	v_add_co_u32_e32 v16, vcc, v16, v14
	s_nop 1
	v_addc_co_u32_e32 v17, vcc, 0, v17, vcc
	s_waitcnt lgkmcnt(0)
	v_max_u32_e32 v6, v6, v7
	v_max_u32_e32 v8, v8, v9
	v_max_u32_e32 v10, v10, v11
	v_max_u32_e32 v12, v12, v13
	v_max_u32_e32 v6, v6, v8
	v_max_u32_e32 v10, v10, v12
	v_max_u32_e32 v6, v6, v10
	global_atomic_umax v[16:17], v6, off
	s_or_b64 exec, exec, s[2:3]
.Lmn_wait:
	s_barrier
	s_mov_b64 s[2:3], exec
	s_branch .LBB0_102
.Lmn_old:
	s_and_saveexec_b64 s[2:3], s[4:5]
	s_cbranch_execz .LBB0_102
	s_ashr_i32 s14, s10, 8
	s_andn2_b32 s14, s14, 31
	v_add_u32_e32 v4, s14, v35
	v_ashrrev_i32_e32 v5, 31, v4
	v_lshl_add_u64 v[4:5], v[4:5], 2, s[6:7]
	s_ashr_i32 s10, s10, 9
	global_atomic_umax v[4:5], v40, off
	global_atomic_umax v[4:5], v41, off offset:16
	global_atomic_umax v[4:5], v42, off offset:32
	global_atomic_umax v[4:5], v43, off offset:48
	global_atomic_umax v[4:5], v44, off offset:64
	global_atomic_umax v[4:5], v45, off offset:80
	global_atomic_umax v[4:5], v46, off offset:96
	global_atomic_umax v[4:5], v47, off offset:112
	s_and_b32 s10, s10, -16
	v_add_u32_e32 v4, s10, v35
	v_ashrrev_i32_e32 v5, 31, v4
	v_lshl_add_u64 v[4:5], v[4:5], 2, s[8:9]
	global_atomic_umax v[4:5], v36, off
	global_atomic_umax v[4:5], v37, off offset:16
	global_atomic_umax v[4:5], v38, off offset:32
	global_atomic_umax v[4:5], v39, off offset:48
	s_branch .LBB0_102

.LBB0_172:
	s_lshl_b32 s98, s80, 6
	s_sub_i32 s96, s89, 64
	s_sub_i32 s98, s98, 64
	s_min_i32 s96, s96, s98
	s_mul_i32 s96, s96, 0x6000
	s_lshl_b32 s97, s88, 15
	s_add_i32 s97, s83, s97
	v_add_u32_e32 v242, s96, v150
	v_add_u32_e32 v243, s96, v154
	v_add_u32_e32 v244, s96, v152
	v_add_u32_e32 v245, s96, v156
	v_add_u32_e32 v246, 0x100, v244
	v_add_u32_e32 v247, 0x100, v245
.LBB0_174:
	ds_read_b128 v[8:11], v206 offset:0
	s_add_i32 s91, s82, s89
	v_lshl_add_u32 v208, s0, 15, v180
	ds_read_b128 v[4:7], v206 offset:0x400
	s_add_i32 s28, s89, 0xffffff80
	s_add_i32 s2, s91, 0xffffff80
	s_add_i32 s0, s91, 0xffffff9f
	ds_read_b64_tr_b16 v[136:137], v208 offset:0
	s_cmp_gt_i32 s0, s86
	ds_read_b64_tr_b16 v[138:139], v208 offset:0x800
	s_cselect_b64 s[8:9], -1, 0
	s_cmp_lt_i32 s2, s87
	ds_read_b64_tr_b16 v[140:141], v208 offset:0x200
	s_cselect_b64 s[0:1], -1, 0
	s_cmp_ge_i32 s2, s87
	ds_read_b64_tr_b16 v[142:143], v208 offset:0xa00
	s_cselect_b64 s[2:3], -1, 0
	ds_read_b64_tr_b16 v[12:13], v208 offset:0x400
	s_and_b64 vcc, s[8:9], s[2:3]
	ds_read_b64_tr_b16 v[14:15], v208 offset:0xc00
	v_cndmask_b32_e32 v0, 0, v183, vcc
	v_cndmask_b32_e32 v1, 0, v184, vcc
	ds_read_b64_tr_b16 v[132:133], v208 offset:0x600
	v_cndmask_b32_e64 v0, v181, v0, s[8:9]
	v_cndmask_b32_e64 v1, v182, v1, s[8:9]
	v_mov_b32_e32 v2, v3
	ds_read_b64_tr_b16 v[134:135], v208 offset:0xe00
	ds_read_b128 v[210:213], v186 offset:0
	ds_read_b128 v[214:217], v187 offset:0
	ds_read_b128 v[218:221], v188 offset:0
	ds_read_b128 v[222:225], v189 offset:0
	s_nop 1
	v_mfma_f32_32x32x16_bf16 v[80:95], v[128:131], v[0:3], 0
	s_add_i32 m0, s83, 0x1c000
	s_nop 0
	global_load_lds_dwordx4 v242, s[74:75]
	s_waitcnt lgkmcnt(3)
	v_mfma_f32_32x32x16_bf16 v[80:95], v[210:213], v[96:99], v[80:95]
	ds_read_b128 v[210:213], v186 offset:0x80
	s_add_i32 m0, s83, 0x1c400
	s_nop 0
	global_load_lds_dwordx4 v243, s[74:75]
	s_waitcnt lgkmcnt(3)
	v_mfma_f32_32x32x16_bf16 v[80:95], v[214:217], v[100:103], v[80:95]
	ds_read_b128 v[214:217], v187 offset:0x80
	s_waitcnt lgkmcnt(3)
	v_mfma_f32_32x32x16_bf16 v[80:95], v[218:221], v[104:107], v[80:95]
	ds_read_b128 v[218:221], v188 offset:0x80
	s_waitcnt lgkmcnt(3)
	v_mfma_f32_32x32x16_bf16 v[80:95], v[222:225], v[108:111], v[80:95]
	ds_read_b128 v[222:225], v189 offset:0x80
	s_waitcnt lgkmcnt(3)
	v_mfma_f32_32x32x16_bf16 v[80:95], v[210:213], v[112:115], v[80:95]
	s_waitcnt lgkmcnt(2)
	v_mfma_f32_32x32x16_bf16 v[80:95], v[214:217], v[116:119], v[80:95]
	s_waitcnt lgkmcnt(1)
	v_mfma_f32_32x32x16_bf16 v[80:95], v[218:221], v[120:123], v[80:95]
	s_waitcnt lgkmcnt(0)
	v_mfma_f32_32x32x16_bf16 v[80:95], v[222:225], v[124:127], v[80:95]
	v_cvt_f32_u32_e32 v0, s28
	s_and_b64 s[2:3], s[8:9], s[0:1]
	s_mov_b64 s[0:1], -1
	s_andn2_b64 vcc, exec, s[2:3]
	v_sub_f32_e32 v1, v185, v0
	s_cbranch_vccz .LBB0_176
	v_cndmask_b32_e64 v0, -v148, v148, s[8:9]
	v_mul_f32_e32 v0, v1, v0
	s_mov_b64 s[0:1], 0

.LBB0_178:
	v_sub_f32_e32 v0, v0, v203
	v_mul_f32_e32 v0, 0x3e0293ee, v0
	s_waitcnt lgkmcnt(4)
	v_mfma_f32_32x32x16_bf16 v[32:47], v[8:11], v[136:139], v[32:47]
	ds_read_b64_tr_b16 v[136:137], v208 offset:0x1000
	ds_read_b64_tr_b16 v[138:139], v208 offset:0x1800
	v_fmamk_f32 v1, v80, 0x3e0293ee, v0
	v_exp_f32_e32 v209, v1
	v_mfma_f32_32x32x16_bf16 v[16:31], v[8:11], v[140:143], v[16:31]
	ds_read_b64_tr_b16 v[140:141], v208 offset:0x1200
	ds_read_b64_tr_b16 v[142:143], v208 offset:0x1a00
	v_fmamk_f32 v1, v81, 0x3e0293ee, v0
	v_exp_f32_e32 v210, v1
	s_waitcnt lgkmcnt(4)
	v_mfma_f32_32x32x16_bf16 v[64:79], v[8:11], v[12:15], v[64:79]
	v_fmamk_f32 v1, v82, 0x3e0293ee, v0
	v_exp_f32_e32 v211, v1
	v_mfma_f32_32x32x16_bf16 v[48:63], v[8:11], v[132:135], v[48:63]
	s_mov_b32 m0, s97
	s_nop 0
	global_load_lds_dwordx4 v244, s[76:77]
	ds_read_b128 v[8:11], v206 offset:0x800
	ds_read_b64_tr_b16 v[12:13], v208 offset:0x1400
	ds_read_b64_tr_b16 v[14:15], v208 offset:0x1c00
	ds_read_b64_tr_b16 v[132:133], v208 offset:0x1600
	ds_read_b64_tr_b16 v[134:135], v208 offset:0x1e00
	v_fmamk_f32 v1, v83, 0x3e0293ee, v0
	v_exp_f32_e32 v212, v1
	s_waitcnt lgkmcnt(5)
	v_mfma_f32_32x32x16_bf16 v[32:47], v[4:7], v[136:139], v[32:47]
	ds_read_b64_tr_b16 v[136:137], v208 offset:0x2000
	ds_read_b64_tr_b16 v[138:139], v208 offset:0x2800
	v_fmamk_f32 v1, v84, 0x3e0293ee, v0
	v_exp_f32_e32 v213, v1
	v_mfma_f32_32x32x16_bf16 v[16:31], v[4:7], v[140:143], v[16:31]
	s_add_i32 m0, s97, 0x400
	s_nop 0
	global_load_lds_dwordx4 v245, s[76:77]
	ds_read_b64_tr_b16 v[140:141], v208 offset:0x2200
	ds_read_b64_tr_b16 v[142:143], v208 offset:0x2a00
	v_fmamk_f32 v1, v85, 0x3e0293ee, v0
	v_exp_f32_e32 v214, v1
	s_waitcnt lgkmcnt(4)
	v_mfma_f32_32x32x16_bf16 v[64:79], v[4:7], v[12:15], v[64:79]
	v_fmamk_f32 v1, v86, 0x3e0293ee, v0
	v_exp_f32_e32 v215, v1
	v_mfma_f32_32x32x16_bf16 v[48:63], v[4:7], v[132:135], v[48:63]
	s_add_i32 m0, s97, 0x4000
	s_nop 0
	global_load_lds_dwordx4 v246, s[76:77]
	ds_read_b128 v[4:7], v206 offset:0xc00
	ds_read_b64_tr_b16 v[12:13], v208 offset:0x2400
	ds_read_b64_tr_b16 v[14:15], v208 offset:0x2c00
	ds_read_b64_tr_b16 v[132:133], v208 offset:0x2600
	ds_read_b64_tr_b16 v[134:135], v208 offset:0x2e00
	v_fmamk_f32 v1, v87, 0x3e0293ee, v0
	v_exp_f32_e32 v216, v1
	s_waitcnt lgkmcnt(5)
	v_mfma_f32_32x32x16_bf16 v[32:47], v[8:11], v[136:139], v[32:47]
	ds_read_b64_tr_b16 v[136:137], v208 offset:0x3000
	ds_read_b64_tr_b16 v[138:139], v208 offset:0x3800
	v_fmamk_f32 v1, v88, 0x3e0293ee, v0
	v_exp_f32_e32 v217, v1
	v_mfma_f32_32x32x16_bf16 v[16:31], v[8:11], v[140:143], v[16:31]
	s_add_i32 m0, s97, 0x4400
	s_nop 0
	global_load_lds_dwordx4 v247, s[76:77]
	ds_read_b64_tr_b16 v[140:141], v208 offset:0x3200
	ds_read_b64_tr_b16 v[142:143], v208 offset:0x3a00
	v_fmamk_f32 v1, v89, 0x3e0293ee, v0
	v_exp_f32_e32 v218, v1
	s_waitcnt lgkmcnt(4)
	v_mfma_f32_32x32x16_bf16 v[64:79], v[8:11], v[12:15], v[64:79]
	v_fmamk_f32 v1, v90, 0x3e0293ee, v0
	v_exp_f32_e32 v219, v1
	v_mfma_f32_32x32x16_bf16 v[48:63], v[8:11], v[132:135], v[48:63]
	ds_read_b64_tr_b16 v[8:9], v208 offset:0x3400
	ds_read_b64_tr_b16 v[10:11], v208 offset:0x3c00
	ds_read_b64_tr_b16 v[12:13], v208 offset:0x3600
	ds_read_b64_tr_b16 v[14:15], v208 offset:0x3e00
	v_fmamk_f32 v1, v91, 0x3e0293ee, v0
	v_exp_f32_e32 v220, v1
	s_waitcnt lgkmcnt(4)
	v_mfma_f32_32x32x16_bf16 v[32:47], v[4:7], v[136:139], v[32:47]
	v_fmamk_f32 v1, v92, 0x3e0293ee, v0
	v_exp_f32_e32 v221, v1
	v_fmamk_f32 v1, v93, 0x3e0293ee, v0
	v_exp_f32_e32 v222, v1
	s_waitcnt lgkmcnt(0)
	v_mfma_f32_32x32x16_bf16 v[16:31], v[4:7], v[140:143], v[16:31]
	v_fmamk_f32 v1, v94, 0x3e0293ee, v0
	v_fmac_f32_e32 v0, 0x3e0293ee, v95
	v_exp_f32_e32 v223, v1
	v_exp_f32_e32 v224, v0
	v_cvt_pk_bf16_f32 v248, v209, v210
	v_cvt_pk_bf16_f32 v249, v211, v212
	v_cvt_pk_bf16_f32 v250, v213, v214
	v_cvt_pk_bf16_f32 v251, v215, v216
	v_mfma_f32_32x32x16_bf16 v[64:79], v[4:7], v[8:11], v[64:79]
	s_add_i32 s0, s88, 1
	s_nop 0
	v_permlane32_swap_b32_e32 v248, v250
	v_permlane32_swap_b32_e32 v249, v251
	ds_write_b128 v204, v[248:251]
	v_cvt_pk_bf16_f32 v248, v217, v218
	v_cvt_pk_bf16_f32 v249, v219, v220
	v_cvt_pk_bf16_f32 v250, v221, v222
	v_cvt_pk_bf16_f32 v251, v223, v224
	v_mfma_f32_32x32x16_bf16 v[48:63], v[4:7], v[12:15], v[48:63]
	s_cmp_lg_u32 s88, 2
	s_nop 0
	v_permlane32_swap_b32_e32 v248, v250
	v_permlane32_swap_b32_e32 v249, v251
	ds_write_b128 v204, v[248:251] offset:1024
	s_cselect_b32 s28, s0, 0
	s_waitcnt vmcnt(4) lgkmcnt(0)
	s_barrier
	s_cmp_ge_i32 s90, s80
	s_cselect_b64 s[2:3], -1, 0
	s_lshl_b32 s98, s80, 6
	s_sub_i32 s98, s98, 64
	s_min_i32 s96, s89, s98
	s_mul_i32 s96, s96, 0x6000
	s_lshl_b32 s97, s28, 15
	s_add_i32 s97, s83, s97
	v_add_u32_e32 v242, s96, v150
	v_add_u32_e32 v243, s96, v154
	v_add_u32_e32 v244, s96, v152
	v_add_u32_e32 v245, s96, v156
	v_add_u32_e32 v246, 0x100, v244
	v_add_u32_e32 v247, 0x100, v245
.LBB0_180:
	ds_read_b128 v[8:11], v202 offset:0
	v_lshl_add_u32 v208, s29, 15, v180
	ds_read_b128 v[4:7], v202 offset:0x400
	s_sub_i32 s29, s89, 64
	s_sub_i32 s92, s91, 64
	s_sub_i32 s0, s91, 33
	ds_read_b64_tr_b16 v[136:137], v208 offset:0
	s_cmp_gt_i32 s0, s86
	ds_read_b64_tr_b16 v[138:139], v208 offset:0x800
	s_cselect_b64 s[8:9], -1, 0
	s_cmp_lt_i32 s92, s87
	ds_read_b64_tr_b16 v[140:141], v208 offset:0x200
	s_cselect_b64 s[0:1], -1, 0
	s_cmp_ge_i32 s92, s87
	ds_read_b64_tr_b16 v[142:143], v208 offset:0xa00
	s_cselect_b64 s[92:93], -1, 0
	ds_read_b64_tr_b16 v[12:13], v208 offset:0x400
	s_and_b64 vcc, s[8:9], s[92:93]
	ds_read_b64_tr_b16 v[14:15], v208 offset:0xc00
	v_cndmask_b32_e32 v0, 0, v183, vcc
	v_cndmask_b32_e32 v1, 0, v184, vcc
	ds_read_b64_tr_b16 v[132:133], v208 offset:0x600
	v_cndmask_b32_e64 v0, v181, v0, s[8:9]
	v_cndmask_b32_e64 v1, v182, v1, s[8:9]
	v_mov_b32_e32 v2, v3
	ds_read_b64_tr_b16 v[134:135], v208 offset:0xe00
	ds_read_b128 v[226:229], v186 offset:0x4000
	ds_read_b128 v[230:233], v187 offset:0x4000
	ds_read_b128 v[234:237], v188 offset:0x4000
	ds_read_b128 v[238:241], v189 offset:0x4000
	s_nop 1
	v_mfma_f32_32x32x16_bf16 v[80:95], v[128:131], v[0:3], 0
	s_mov_b32 m0, s84
	s_nop 0
	global_load_lds_dwordx4 v242, s[74:75]
	s_waitcnt lgkmcnt(3)
	v_mfma_f32_32x32x16_bf16 v[80:95], v[226:229], v[96:99], v[80:95]
	v_add_f32_e32 v254, 0, v209
	v_add_f32_e32 v254, v210, v254
	ds_read_b128 v[226:229], v186 offset:0x4080
	s_mov_b32 m0, s85
	s_nop 0
	global_load_lds_dwordx4 v243, s[74:75]
	s_waitcnt lgkmcnt(3)
	v_mfma_f32_32x32x16_bf16 v[80:95], v[230:233], v[100:103], v[80:95]
	v_add_f32_e32 v254, v211, v254
	v_add_f32_e32 v254, v212, v254
	ds_read_b128 v[230:233], v187 offset:0x4080
	s_waitcnt lgkmcnt(3)
	v_mfma_f32_32x32x16_bf16 v[80:95], v[234:237], v[104:107], v[80:95]
	v_add_f32_e32 v254, v213, v254
	v_add_f32_e32 v254, v214, v254
	ds_read_b128 v[234:237], v188 offset:0x4080
	s_waitcnt lgkmcnt(3)
	v_mfma_f32_32x32x16_bf16 v[80:95], v[238:241], v[108:111], v[80:95]
	v_add_f32_e32 v254, v215, v254
	v_add_f32_e32 v254, v216, v254
	ds_read_b128 v[238:241], v189 offset:0x4080
	s_waitcnt lgkmcnt(3)
	v_mfma_f32_32x32x16_bf16 v[80:95], v[226:229], v[112:115], v[80:95]
	v_add_f32_e32 v254, v217, v254
	v_add_f32_e32 v254, v218, v254
	s_waitcnt lgkmcnt(2)
	v_mfma_f32_32x32x16_bf16 v[80:95], v[230:233], v[116:119], v[80:95]
	v_add_f32_e32 v254, v219, v254
	v_add_f32_e32 v254, v220, v254
	s_waitcnt lgkmcnt(1)
	v_mfma_f32_32x32x16_bf16 v[80:95], v[234:237], v[120:123], v[80:95]
	v_add_f32_e32 v254, v221, v254
	v_add_f32_e32 v254, v222, v254
	s_waitcnt lgkmcnt(0)
	v_mfma_f32_32x32x16_bf16 v[80:95], v[238:241], v[124:127], v[80:95]
	v_add_f32_e32 v254, v223, v254
	v_add_f32_e32 v254, v224, v254
	v_cvt_f32_u32_e32 v0, s29
	s_and_b64 s[92:93], s[8:9], s[0:1]
	s_mov_b64 s[0:1], -1
	s_andn2_b64 vcc, exec, s[92:93]
	v_sub_f32_e32 v0, v185, v0
	s_cbranch_vccz .LBB0_182
	v_cndmask_b32_e64 v1, -v148, v148, s[8:9]
	v_mul_f32_e32 v1, v0, v1
	s_mov_b64 s[0:1], 0

.LBB0_184:
	s_waitcnt lgkmcnt(4)
	v_sub_f32_e32 v1, v1, v203
	v_add_f32_e32 v0, v207, v254
	v_mul_f32_e32 v1, 0x3e0293ee, v1
	v_mfma_f32_32x32x16_bf16 v[32:47], v[8:11], v[136:139], v[32:47]
	ds_read_b64_tr_b16 v[136:137], v208 offset:0x1000
	v_fmamk_f32 v2, v80, 0x3e0293ee, v1
	ds_read_b64_tr_b16 v[138:139], v208 offset:0x1800
	v_exp_f32_e32 v2, v2
	v_fmamk_f32 v81, v81, 0x3e0293ee, v1
	v_exp_f32_e32 v159, v81
	v_add_f32_e32 v80, 0, v2
	v_mfma_f32_32x32x16_bf16 v[16:31], v[8:11], v[140:143], v[16:31]
	ds_read_b64_tr_b16 v[140:141], v208 offset:0x1200
	ds_read_b64_tr_b16 v[142:143], v208 offset:0x1a00
	s_waitcnt lgkmcnt(4)
	v_add_f32_e32 v80, v159, v80
	v_mfma_f32_32x32x16_bf16 v[64:79], v[8:11], v[12:15], v[64:79]
	v_mfma_f32_32x32x16_bf16 v[48:63], v[8:11], v[132:135], v[48:63]
	s_mov_b32 m0, s97
	s_nop 0
	global_load_lds_dwordx4 v244, s[76:77]
	v_fmamk_f32 v8, v82, 0x3e0293ee, v1
	v_exp_f32_e32 v209, v8
	v_fmamk_f32 v9, v83, 0x3e0293ee, v1
	v_exp_f32_e32 v210, v9
	v_add_f32_e32 v8, v209, v80
	v_add_f32_e32 v132, v210, v8
	ds_read_b128 v[8:11], v202 offset:0x800
	ds_read_b64_tr_b16 v[12:13], v208 offset:0x1400
	ds_read_b64_tr_b16 v[14:15], v208 offset:0x1c00
	ds_read_b64_tr_b16 v[80:81], v208 offset:0x1600
	ds_read_b64_tr_b16 v[82:83], v208 offset:0x1e00
	s_waitcnt lgkmcnt(5)
	v_fmamk_f32 v84, v84, 0x3e0293ee, v1
	v_mfma_f32_32x32x16_bf16 v[16:31], v[4:7], v[140:143], v[16:31]
	v_exp_f32_e32 v140, v84
	v_fmamk_f32 v85, v85, 0x3e0293ee, v1
	v_exp_f32_e32 v141, v85
	v_add_f32_e32 v84, v140, v132
	ds_read_b64_tr_b16 v[132:133], v208 offset:0x2000
	ds_read_b64_tr_b16 v[134:135], v208 offset:0x2800
	v_mfma_f32_32x32x16_bf16 v[32:47], v[4:7], v[136:139], v[32:47]
	s_add_i32 m0, s97, 0x400
	s_nop 0
	global_load_lds_dwordx4 v245, s[76:77]
	ds_read_b64_tr_b16 v[136:137], v208 offset:0x2200
	ds_read_b64_tr_b16 v[138:139], v208 offset:0x2a00
	s_waitcnt lgkmcnt(4)
	v_add_f32_e32 v84, v141, v84
	v_mfma_f32_32x32x16_bf16 v[64:79], v[4:7], v[12:15], v[64:79]
	v_mfma_f32_32x32x16_bf16 v[48:63], v[4:7], v[80:83], v[48:63]
	s_add_i32 m0, s97, 0x4000
	s_nop 0
	global_load_lds_dwordx4 v246, s[76:77]
	v_fmamk_f32 v4, v86, 0x3e0293ee, v1
	v_exp_f32_e32 v142, v4
	v_fmamk_f32 v5, v87, 0x3e0293ee, v1
	v_exp_f32_e32 v143, v5
	v_add_f32_e32 v4, v142, v84
	v_add_f32_e32 v84, v143, v4
	ds_read_b128 v[4:7], v202 offset:0xc00
	ds_read_b64_tr_b16 v[12:13], v208 offset:0x2400
	ds_read_b64_tr_b16 v[14:15], v208 offset:0x2c00
	ds_read_b64_tr_b16 v[80:81], v208 offset:0x2600
	ds_read_b64_tr_b16 v[82:83], v208 offset:0x2e00
	s_waitcnt lgkmcnt(5)
	v_fmamk_f32 v85, v88, 0x3e0293ee, v1
	v_exp_f32_e32 v88, v85
	v_fmamk_f32 v85, v89, 0x3e0293ee, v1
	v_exp_f32_e32 v89, v85
	v_mfma_f32_32x32x16_bf16 v[32:47], v[8:11], v[132:135], v[32:47]
	v_add_f32_e32 v84, v88, v84
	v_mfma_f32_32x32x16_bf16 v[16:31], v[8:11], v[136:139], v[16:31]
	s_add_i32 m0, s97, 0x4400
	s_nop 0
	global_load_lds_dwordx4 v247, s[76:77]
	v_add_f32_e32 v136, v89, v84
	ds_read_b64_tr_b16 v[84:85], v208 offset:0x3000
	ds_read_b64_tr_b16 v[86:87], v208 offset:0x3800
	ds_read_b64_tr_b16 v[132:133], v208 offset:0x3200
	ds_read_b64_tr_b16 v[134:135], v208 offset:0x3a00
	s_waitcnt lgkmcnt(4)
	v_mfma_f32_32x32x16_bf16 v[64:79], v[8:11], v[12:15], v[64:79]
	v_mfma_f32_32x32x16_bf16 v[48:63], v[8:11], v[80:83], v[48:63]
	v_fmamk_f32 v8, v90, 0x3e0293ee, v1
	v_exp_f32_e32 v80, v8
	v_fmamk_f32 v9, v91, 0x3e0293ee, v1
	v_exp_f32_e32 v81, v9
	v_add_f32_e32 v8, v80, v136
	v_add_f32_e32 v82, v81, v8
	ds_read_b64_tr_b16 v[8:9], v208 offset:0x3400
	ds_read_b64_tr_b16 v[10:11], v208 offset:0x3c00
	ds_read_b64_tr_b16 v[12:13], v208 offset:0x3600
	ds_read_b64_tr_b16 v[14:15], v208 offset:0x3e00
	s_waitcnt lgkmcnt(4)
	v_mfma_f32_32x32x16_bf16 v[32:47], v[4:7], v[84:87], v[32:47]
	v_fmamk_f32 v83, v92, 0x3e0293ee, v1
	v_exp_f32_e32 v83, v83
	v_fmamk_f32 v84, v93, 0x3e0293ee, v1
	v_exp_f32_e32 v84, v84
	s_waitcnt lgkmcnt(0)
	v_add_f32_e32 v82, v83, v82
	v_add_f32_e32 v82, v84, v82
	v_mfma_f32_32x32x16_bf16 v[16:31], v[4:7], v[132:135], v[16:31]
	v_cvt_pk_bf16_f32 v248, v2, v159
	v_cvt_pk_bf16_f32 v249, v209, v210
	v_cvt_pk_bf16_f32 v250, v140, v141
	v_cvt_pk_bf16_f32 v251, v142, v143
	v_mfma_f32_32x32x16_bf16 v[64:79], v[4:7], v[8:11], v[64:79]
	s_add_i32 s0, s28, 1
	s_cmp_lg_u32 s28, 2
	s_cselect_b32 s1, s0, 0
	s_addk_i32 s89, 0x80
	s_add_i32 s90, s90, 2
	s_and_b64 vcc, exec, s[2:3]
	v_permlane32_swap_b32_e32 v248, v250
	v_permlane32_swap_b32_e32 v249, v251
	ds_write_b128 v205, v[248:251]
	v_fmamk_f32 v252, v94, 0x3e0293ee, v1
	v_exp_f32_e32 v253, v252
	v_fmac_f32_e32 v1, 0x3e0293ee, v95
	v_exp_f32_e32 v1, v1
	v_mfma_f32_32x32x16_bf16 v[48:63], v[4:7], v[12:15], v[48:63]
	v_add_f32_e32 v252, v253, v82
	v_add_f32_e32 v252, v1, v252
	v_add_f32_e32 v207, v0, v252
	v_cvt_pk_bf16_f32 v248, v88, v89
	v_cvt_pk_bf16_f32 v249, v80, v81
	v_cvt_pk_bf16_f32 v250, v83, v84
	v_cvt_pk_bf16_f32 v251, v253, v1
	s_nop 1
	v_permlane32_swap_b32_e32 v248, v250
	v_permlane32_swap_b32_e32 v249, v251
	ds_write_b128 v205, v[248:251] offset:1024
	s_waitcnt vmcnt(4) lgkmcnt(0)
	s_barrier
	s_cbranch_vccnz .LBB0_187
	s_mov_b32 s0, s88
	s_mov_b32 s29, s28
	s_mov_b32 s88, s1
	s_branch .LBB0_172

; __device__ __forceinline__ void attn_body3(const bf16* __restrict__ Qb, const bf16* __restrict__ Kh, const bf16* __restrict__ Vh,
;                                            bf16* __restrict__ Ob, int seq, int qpos0, float slS, float mraw, char* lds, const int tid) {
;     ...
;   { const int vbp_ = vb0 + vprev * 32768; const char* xr_ = lds + xoff + 16384;
;     { const bf16x8 x_ = *(const bf16x8*)(xr_); pv_ks<0>(o, vbp_, x_); } { const bf16x8 x_ = *(const bf16x8*)(xr_ + 1024); pv_ks<1>(o, vbp_, x_); }
;     { const bf16x8 x_ = *(const bf16x8*)(xr_ + 2048); pv_ks<2>(o, vbp_, x_); } { const bf16x8 x_ = *(const bf16x8*)(xr_ + 3072); pv_ks<3>(o, vbp_, x_); } }
;   { auto rr = __builtin_amdgcn_permlane32_swap(__float_as_uint(lsum), __float_as_uint(lsum), false, false);
;     lsum = __uint_as_float(rr[0]) + __uint_as_float(rr[1]); }
;   __syncthreads();
;   float* li = (float*)(lds + A3_X) + pair * 64;
;   if (hi == 0) li[role * 32 + r32] = lsum;
.LBB0_188:
	v_add_u32_e32 v1, 0x24000, v179
	v_add_u32_e32 v0, s0, v180
	ds_read_b128 v[4:7], v1
	ds_read_b64_tr_b16 v[8:9], v0 offset:0
	ds_read_b64_tr_b16 v[10:11], v0 offset:0x800
	ds_read_b64_tr_b16 v[12:13], v0 offset:0x200
	ds_read_b64_tr_b16 v[14:15], v0 offset:0xa00
	ds_read_b64_tr_b16 v[80:81], v0 offset:0x400
	ds_read_b64_tr_b16 v[82:83], v0 offset:0xc00
	ds_read_b64_tr_b16 v[84:85], v0 offset:0x600
	ds_read_b64_tr_b16 v[86:87], v0 offset:0xe00
	s_waitcnt lgkmcnt(0)
	v_add_u32_e32 v1, 0x24400, v179
	s_waitcnt lgkmcnt(0)
	v_mfma_f32_32x32x16_bf16 v[32:47], v[4:7], v[8:11], v[32:47]
	v_mfma_f32_32x32x16_bf16 v[16:31], v[4:7], v[12:15], v[16:31]
	v_mfma_f32_32x32x16_bf16 v[64:79], v[4:7], v[80:83], v[64:79]
	v_mfma_f32_32x32x16_bf16 v[48:63], v[4:7], v[84:87], v[48:63]
	ds_read_b128 v[4:7], v1
	ds_read_b64_tr_b16 v[8:9], v0 offset:0x1000
	ds_read_b64_tr_b16 v[10:11], v0 offset:0x1800
	ds_read_b64_tr_b16 v[12:13], v0 offset:0x1200
	ds_read_b64_tr_b16 v[14:15], v0 offset:0x1a00
	ds_read_b64_tr_b16 v[80:81], v0 offset:0x1400
	ds_read_b64_tr_b16 v[82:83], v0 offset:0x1c00
	ds_read_b64_tr_b16 v[84:85], v0 offset:0x1600
	ds_read_b64_tr_b16 v[86:87], v0 offset:0x1e00
	s_waitcnt lgkmcnt(0)
	v_add_u32_e32 v1, 0x24800, v179
	s_waitcnt lgkmcnt(0)
	v_mfma_f32_32x32x16_bf16 v[32:47], v[4:7], v[8:11], v[32:47]
	v_mfma_f32_32x32x16_bf16 v[16:31], v[4:7], v[12:15], v[16:31]
	v_mfma_f32_32x32x16_bf16 v[64:79], v[4:7], v[80:83], v[64:79]
	v_mfma_f32_32x32x16_bf16 v[48:63], v[4:7], v[84:87], v[48:63]
	ds_read_b128 v[4:7], v1
	ds_read_b64_tr_b16 v[8:9], v0 offset:0x2000
	ds_read_b64_tr_b16 v[10:11], v0 offset:0x2800
	ds_read_b64_tr_b16 v[12:13], v0 offset:0x2200
	ds_read_b64_tr_b16 v[14:15], v0 offset:0x2a00
	ds_read_b64_tr_b16 v[80:81], v0 offset:0x2400
	ds_read_b64_tr_b16 v[82:83], v0 offset:0x2c00
	ds_read_b64_tr_b16 v[84:85], v0 offset:0x2600
	ds_read_b64_tr_b16 v[86:87], v0 offset:0x2e00
	s_waitcnt lgkmcnt(0)
	v_add_u32_e32 v1, 0x24c00, v179
	s_waitcnt lgkmcnt(0)
	v_mfma_f32_32x32x16_bf16 v[32:47], v[4:7], v[8:11], v[32:47]
	v_mfma_f32_32x32x16_bf16 v[16:31], v[4:7], v[12:15], v[16:31]
	v_mfma_f32_32x32x16_bf16 v[64:79], v[4:7], v[80:83], v[64:79]
	v_mfma_f32_32x32x16_bf16 v[48:63], v[4:7], v[84:87], v[48:63]
	ds_read_b128 v[4:7], v1
	ds_read_b64_tr_b16 v[8:9], v0 offset:0x3000
	ds_read_b64_tr_b16 v[10:11], v0 offset:0x3800
	ds_read_b64_tr_b16 v[12:13], v0 offset:0x3200
	ds_read_b64_tr_b16 v[14:15], v0 offset:0x3a00
	ds_read_b64_tr_b16 v[80:81], v0 offset:0x3400
	ds_read_b64_tr_b16 v[82:83], v0 offset:0x3c00
	ds_read_b64_tr_b16 v[84:85], v0 offset:0x3600
	ds_read_b64_tr_b16 v[86:87], v0 offset:0x3e00
	s_waitcnt lgkmcnt(0)
	s_waitcnt lgkmcnt(0)
	v_mfma_f32_32x32x16_bf16 v[32:47], v[4:7], v[8:11], v[32:47]
	s_lshl_b32 s0, s81, 8
	v_mov_b32_e32 v0, v207
	s_add_i32 s2, s0, 0
	s_nop 0
	v_permlane32_swap_b32_e32 v207, v0
	s_add_i32 s2, s2, 0x20000
	v_mfma_f32_32x32x16_bf16 v[16:31], v[4:7], v[12:15], v[16:31]
	s_waitcnt vmcnt(0)
	s_barrier
	v_mfma_f32_32x32x16_bf16 v[64:79], v[4:7], v[80:83], v[64:79]
	v_mfma_f32_32x32x16_bf16 v[48:63], v[4:7], v[84:87], v[48:63]
	s_and_saveexec_b64 s[0:1], s[6:7]
	s_cbranch_execz .LBB0_146
	v_add_f32_e32 v0, v207, v0
	v_lshl_add_u32 v1, v147, 2, s2
	ds_write_b32 v1, v0
	s_branch .LBB0_146

; __device__ __forceinline__ void grid_barrier(unsigned* cnt, unsigned target, int tid) {
;   asm volatile("s_waitcnt vmcnt(0)" ::: "memory");
;   __syncthreads();
;   if (tid == 0) {
;     __builtin_amdgcn_fence(__ATOMIC_RELEASE, "agent");
;     asm volatile("s_waitcnt vmcnt(0)" ::: "memory");
;     __hip_atomic_fetch_add(cnt, 1u, __ATOMIC_RELAXED, __HIP_MEMORY_SCOPE_AGENT);
;     unsigned spins = 0;
;     while (__hip_atomic_load(cnt, __ATOMIC_RELAXED, __HIP_MEMORY_SCOPE_AGENT) < target) {
;       __builtin_amdgcn_s_sleep(1);
;       if (++spins > (1u << 27)) break;
;     }
;     __builtin_amdgcn_fence(__ATOMIC_ACQUIRE, "agent");
;   }
;   __syncthreads();
; __global__ __launch_bounds__(512, 2)
; void hybrid_megakernel(Params p_in) {
;     ...
;     const bool empty_phase = (ph > 0) && ((ph - 1) % PH_PER_LAYER == 7) && ((ph - 1) / PH_PER_LAYER + 1 < DEPTH);
;     if (coop && ph + 1 < ph_end && !empty_phase) {
;       if (ph == 0) cg::this_grid().sync();
;       else { ++nbar; grid_barrier((unsigned*)(ws + WS_BAR), (unsigned)nbar * (unsigned)G, tid); }
;     }
.LBB0_378:
	v_readlane_b32 s0, v255, 16
	v_readlane_b32 s1, v255, 17
	s_and_b64 vcc, exec, s[0:1]
	s_cbranch_vccz .LBB0_396
	s_cmp_gt_i32 s12, 0
	s_cselect_b64 s[0:1], -1, 0
	s_sub_i32 s2, 0, s12
	s_and_b32 s2, s2, 7
	s_cmp_eq_u32 s2, 0
	s_cselect_b64 s[2:3], -1, 0
	s_cmp_lt_u32 s12, 9
	s_cselect_b64 s[4:5], -1, 0
	s_and_b64 s[2:3], s[4:5], s[2:3]
	s_and_b64 s[0:1], s[0:1], s[2:3]
	s_add_i32 s8, s12, 1
	s_cmp_ge_i32 s8, s13
	s_cselect_b64 s[2:3], -1, 0
	s_or_b64 s[0:1], s[2:3], s[0:1]
	s_and_b64 vcc, exec, s[0:1]
	s_cbranch_vccnz .LBB0_397
	s_waitcnt vmcnt(0)
	v_readlane_b32 s0, v255, 18
	s_add_i32 s9, s0, 1
	v_cmp_eq_u32_e32 vcc, 0, v144
	s_waitcnt vmcnt(0) lgkmcnt(0)
	s_barrier
	s_and_saveexec_b64 s[0:1], vcc
	s_cbranch_execz .LBB0_401
	s_mov_b64 s[4:5], exec
	buffer_wbl2 sc1
	s_waitcnt vmcnt(0)
	v_mbcnt_lo_u32_b32 v0, s4, 0
	s_add_u32 s2, s54, 0x5f108400
	v_mbcnt_hi_u32_b32 v0, s5, v0
	s_addc_u32 s3, s55, 0
	v_cmp_eq_u32_e32 vcc, 0, v0
	s_and_saveexec_b64 s[6:7], vcc
	s_cbranch_execz .LBB0_384
	s_bcnt1_i32_b64 s4, s[4:5]
	v_mov_b32_e32 v0, s4
	global_atomic_add v3, v0, s[2:3]

; __global__ __launch_bounds__(512, 2)
; void hybrid_megakernel(Params p_in) {
;     ...
;     if (coop && ph + 1 < ph_end && !empty_phase) {
;       if (ph == 0) cg::this_grid().sync();
;       else { ++nbar; grid_barrier((unsigned*)(ws + WS_BAR), (unsigned)nbar * (unsigned)G, tid); }
;     }
.LBB0_397:
	v_readlane_b32 s9, v255, 18
	s_cbranch_execnz .LBB0_2
	s_branch .LBB0_413
.LBB0_399:
	s_cbranch_execnz .LBB0_2
	s_branch .LBB0_413

; __global__ __launch_bounds__(512, 2)
; void hybrid_megakernel(Params p_in) {
;     ...
;     if (coop && ph + 1 < ph_end && !empty_phase) {
;       if (ph == 0) cg::this_grid().sync();
;       else { ++nbar; grid_barrier((unsigned*)(ws + WS_BAR), (unsigned)nbar * (unsigned)G, tid); }
;     }
.LBB0_401:
	s_or_b64 exec, exec, s[0:1]
	s_barrier
	s_branch .LBB0_399
.LBB0_413:
	s_add_i32 s8, s12, 1
	v_readlane_b32 s9, v255, 18
	s_branch .LBB0_2
